# prologue de-serialisation extended to P4, P3, P1b (all GEMM phase prologues issue their 14 staging DMAs up front)
# baseline (speedup 1.0000x reference)
;     __device__ __forceinline__ unsigned voffA(int R, int C) const { return (unsigned)(R * lda + C) * 2u; }
;     __device__ __forceinline__ unsigned voffB(int R, int C) const { return (unsigned)(R * ldb + C) * 2u; }
;     __device__ __forceinline__ size_t hA() const { return (size_t)HALF * lda * 2; }
;     __device__ __forceinline__ size_t hB() const { return (size_t)HALF * ldb * 2; }
;     __device__ __forceinline__ const char* a(const Unit& u) const { return (const char*)A + (size_t)u.pm * 2 * hA(); }
;     __device__ __forceinline__ const char* b(const Unit& u) const { return (const char*)Bt + (size_t)u.pn * 2 * hB() + (size_t)(u.pm >> gshift) * goff; }
;     __device__ __forceinline__ unsigned voffA(int R, int C) const { return (unsigned)(R * 256 + C) * 2u; }
;     __device__ __forceinline__ unsigned voffB(int R, int C) const { return (unsigned)((256 * (R & 15) + (R >> 4)) * 1024 + C) * 2u; }
;     __device__ __forceinline__ size_t hA() const { return (size_t)HALF * 256 * 2; }
;     __device__ __forceinline__ size_t hB() const { return (size_t)8 * 1024 * 2; }
;     __device__ __forceinline__ const char* a(const Unit& u) const { return (const char*)A + (size_t)u.pm * 2 * hA(); }
;     __device__ __forceinline__ const char* b(const Unit& u) const { return (const char*)Bt + (size_t)((u.pn >> 4) * 4096 + (u.pn & 15) * 16) * 1024 * 2 + (size_t)(u.pm >> 1) * 512; }
;     __device__ __forceinline__ size_t hA() const { return (size_t)HALF * 512 * 2; }
;     ...
;     for (int i = 0; i < 2; ++i) { int R, C; stage_rc(tid * 16 + i * 8192, R, C); const int Rb = Epi::PERM ? ((R & ~31) + perm32(R & 31)) : R;
;         voffA[i] = g.voffA(R, C); voffB[i] = g.voffB(Rb, C); }
;     const size_t kstep = (size_t)(BK * 2);
;     const size_t hstepA = g.hA(), hstepB = g.hB();
;     const unsigned ldsw = (unsigned)wid * 1024u;
;     const int aoff = lds_byte(wr * 64 + fr, fq * 8), boff = lds_byte(wc * 32 + fr, fq * 8);
;     ...
;     const char* cA = g.a(cur); const char* cB = g.b(cur);
;     S.a_ready(cur);
;     PG8_STAGE(PG8_SB(0, 0), cB, voffB); PG8_STAGE(PG8_SB(0, 1), cB + hstepB, voffB); PG8_STAGE(PG8_SA(0, 0), cA, voffA); PG8_STAGE(PG8_SA(0, 1), cA + hstepA, voffA);
;     if (wr == 1) PG8_BAR;
;     PG8_WAIT_V(2); PG8_BAR;
;     PG8_STAGE(PG8_SB(1, 0), cB + kstep, voffB); PG8_STAGE(PG8_SA(1, 0), cA + kstep, voffA); PG8_STAGE(PG8_SB(1, 1), cB + hstepB + kstep, voffB);
.LBB0_347:
	s_mov_b32 s12, -1
	s_lshl_b32 s13, s56, 4
	v_mbcnt_lo_u32_b32 v0, s12, 0
	v_mbcnt_hi_u32_b32 v0, s12, v0
	s_lshl_b32 s12, s56, 8
	v_lshlrev_b32_e32 v1, 4, v0
	v_add_u32_e32 v2, s33, v1
	v_ashrrev_i32_e32 v3, 31, v2
	v_lshrrev_b32_e32 v3, 22, v3
	v_add_u32_e32 v3, v2, v3
	v_ashrrev_i32_e32 v3, 10, v3
	v_mul_i32_i24_e32 v4, 0x400, v3
	v_sub_u32_e32 v4, v2, v4
	v_lshrrev_b32_e32 v5, 4, v4
	v_bitop3_b32 v4, v5, v4, 32 bitop3:0x6c
	v_ashrrev_i32_e32 v6, 31, v4
	v_lshrrev_b32_e32 v6, 26, v6
	v_lshlrev_b32_e32 v5, 3, v3
	v_add_u32_e32 v6, v4, v6
	v_and_b32_e32 v5, -16, v5
	v_ashrrev_i32_e32 v7, 6, v6
	v_add_u32_e32 v5, v7, v5
	v_and_b32_e32 v6, 0xc0, v6
	v_sub_u32_e32 v4, v4, v6
	v_lshlrev_b32_e32 v6, 1, v5
	v_lshrrev_b32_e32 v8, 2, v5
	v_lshlrev_b32_e32 v3, 5, v3
	v_ashrrev_i16_sdwa v4, v140, sext(v4) dst_sel:DWORD dst_unused:UNUSED_PAD src0_sel:DWORD src1_sel:BYTE_0
	v_and_b32_e32 v6, 24, v6
	v_and_b32_e32 v8, 4, v8
	v_and_b32_e32 v7, 3, v7
	v_and_b32_e32 v3, 32, v3
	v_bfe_i32 v4, v4, 0, 16
	v_or3_b32 v7, v7, v8, v6
	v_and_or_b32 v6, v5, s53, v6
	v_add_lshl_u32 v3, v3, v4, 1
	v_lshlrev_b32_e32 v4, 8, v7
	v_lshl_add_u32 v132, v5, 9, v3
	v_and_b32_e32 v4, 0xf00, v4
	v_lshrrev_b32_e32 v5, 4, v6
	v_add_u32_e32 v4, v4, v5
	v_add_u32_e32 v2, 0x2000, v2
	v_lshl_add_u32 v130, v4, 11, v3
	v_ashrrev_i32_e32 v3, 31, v2
	v_lshrrev_b32_e32 v3, 22, v3
	v_add_u32_e32 v3, v2, v3
	v_ashrrev_i32_e32 v3, 10, v3
	v_mul_i32_i24_e32 v4, 0x400, v3
	v_sub_u32_e32 v2, v2, v4
	v_lshrrev_b32_e32 v4, 4, v2
	v_bitop3_b32 v2, v4, v2, 32 bitop3:0x6c
	v_ashrrev_i32_e32 v5, 31, v2
	v_lshrrev_b32_e32 v5, 26, v5
	s_and_b32 s12, s12, 0xfffff000
	s_and_b32 s13, s13, 0xf0
	v_add_u32_e32 v5, v2, v5
	s_or_b32 s12, s12, s13
	v_ashrrev_i32_e32 v6, 6, v5
	v_and_b32_e32 v5, 0xffc0, v5
	s_ashr_i32 s13, s12, 31
	v_lshlrev_b32_e32 v4, 3, v3
	v_sub_u32_e32 v2, v2, v5
	s_ashr_i64 s[16:17], s[0:1], 15
	s_lshl_b64 s[12:13], s[12:13], 11
	v_and_b32_e32 v4, -16, v4
	v_lshrrev_b16_e32 v5, 7, v2
	s_add_u32 s18, s68, s12
	v_add_u32_e32 v4, v6, v4
	v_and_b32_e32 v5, 1, v5
	s_addc_u32 s19, s69, s13
	s_ashr_i32 s12, s1, 1
	v_add_u16_e32 v2, v2, v5
	v_lshlrev_b32_e32 v5, 1, v4
	v_lshrrev_b32_e32 v7, 2, v4
	s_ashr_i32 s13, s12, 31
	v_lshlrev_b32_e32 v3, 5, v3
	v_ashrrev_i16_sdwa v2, v140, sext(v2) dst_sel:DWORD dst_unused:UNUSED_PAD src0_sel:DWORD src1_sel:BYTE_0
	v_and_b32_e32 v5, 24, v5
	v_and_b32_e32 v7, 4, v7
	v_and_b32_e32 v6, 3, v6
	s_lshl_b64 s[12:13], s[12:13], 9
	v_and_b32_e32 v3, 32, v3
	v_bfe_i32 v2, v2, 0, 16
	v_or3_b32 v6, v6, v7, v5
	s_add_u32 s12, s18, s12
	v_and_or_b32 v5, v4, s53, v5
	v_add_lshl_u32 v2, v3, v2, 1
	v_lshlrev_b32_e32 v3, 8, v6
	s_addc_u32 s13, s19, s13
	s_add_i32 s57, s33, 0
	v_lshl_add_u32 v134, v4, 9, v2
	v_and_b32_e32 v3, 0xf00, v3
	v_lshrrev_b32_e32 v4, 4, v5
	s_add_i32 m0, s57, 0x10000
	v_add_u32_e32 v3, v3, v4
	global_load_lds_dwordx4 v130, s[12:13]
	s_add_i32 m0, s57, 0x12000
	v_lshl_add_u32 v136, v3, 11, v2
	s_add_u32 s18, s12, 0x4000
	global_load_lds_dwordx4 v136, s[12:13]
	s_addc_u32 s19, s13, 0
	s_add_i32 m0, s57, 0x14000
	s_nop 0
	global_load_lds_dwordx4 v130, s[18:19]
	s_add_i32 m0, s57, 0x16000
	s_add_u32 s16, s58, s16
	s_addc_u32 s17, s59, s17
	s_add_i32 s60, s57, 0x2000
	global_load_lds_dwordx4 v136, s[18:19]
	s_mov_b32 m0, s57
	s_add_u32 s18, s16, 0x10000
	global_load_lds_dwordx4 v132, s[16:17]
	s_mov_b32 m0, s60
	s_addc_u32 s19, s17, 0
	s_add_i32 s61, s57, 0x4000
	global_load_lds_dwordx4 v134, s[16:17]
	s_mov_b32 m0, s61
	s_add_i32 s66, s57, 0x6000
	global_load_lds_dwordx4 v132, s[18:19]
	s_mov_b32 m0, s66
	s_andn2_b64 vcc, exec, s[4:5]
	global_load_lds_dwordx4 v134, s[18:19]
	s_add_u32 s98, s12, 0x80
	s_addc_u32 s99, s13, 0
	s_add_i32 m0, s57, 0x18000
	s_nop 0
	global_load_lds_dwordx4 v130, s[98:99]
	s_add_i32 m0, s57, 0x1a000
	s_nop 0
	global_load_lds_dwordx4 v136, s[98:99]
	s_add_u32 s98, s16, 0x80
	s_addc_u32 s99, s17, 0
	s_add_i32 m0, s57, 0x8000
	s_nop 0
	global_load_lds_dwordx4 v132, s[98:99]
	s_add_i32 m0, s57, 0xa000
	s_nop 0
	global_load_lds_dwordx4 v134, s[98:99]
	s_add_u32 s98, s12, 0x4080
	s_addc_u32 s99, s13, 0
	s_add_i32 m0, s57, 0x1c000
	s_nop 0
	global_load_lds_dwordx4 v130, s[98:99]
	s_add_i32 m0, s57, 0x1e000
	s_nop 0
	global_load_lds_dwordx4 v136, s[98:99]
	s_cbranch_vccnz .LBB0_349
	s_barrier
;     __device__ __forceinline__ unsigned voffA(int R, int C) const { return (unsigned)(R * lda + C) * 2u; }
;     __device__ __forceinline__ unsigned voffB(int R, int C) const { return (unsigned)(R * ldb + C) * 2u; }
;     __device__ __forceinline__ const char* a(const Unit& u) const { return (const char*)A + (size_t)u.pm * 2 * hA(); }
;     __device__ __forceinline__ const char* b(const Unit& u) const { return (const char*)Bt + (size_t)u.pn * 2 * hB() + (size_t)(u.pm >> gshift) * goff; }
;     __device__ __forceinline__ unsigned voffA(int R, int C) const { return (unsigned)(R * 256 + C) * 2u; }
;     __device__ __forceinline__ unsigned voffB(int R, int C) const { return (unsigned)((256 * (R & 15) + (R >> 4)) * 1024 + C) * 2u; }
;     __device__ __forceinline__ const char* a(const Unit& u) const { return (const char*)A + (size_t)u.pm * 2 * hA(); }
;     __device__ __forceinline__ const char* b(const Unit& u) const { return (const char*)Bt + (size_t)((u.pn >> 4) * 4096 + (u.pn & 15) * 16) * 1024 * 2 + (size_t)(u.pm >> 1) * 512; }
;     __device__ __forceinline__ unsigned voffA(int R, int C) const { return (unsigned)(R * 512 + C) * 2u; }
;     __device__ __forceinline__ unsigned voffB(int R, int C) const { return (unsigned)(R * 8192 + C) * 2u; }
;     __device__ __forceinline__ const char* a(const Unit&) const { return (const char*)A; }
; #define PG8_BAR __builtin_amdgcn_s_barrier()
;     ...
;     const int aoff = lds_byte(wr * 64 + fr, fq * 8), boff = lds_byte(wc * 32 + fr, fq * 8);
;     ...
;     Unit cur, nxt; int ui = 0;
;     if (!S.next(0, cur)) return;
;     f32x4 acc[2][2][4][2];
; #pragma unroll
;     for (int a = 0; a < 2; ++a)
; #pragma unroll
;         for (int b = 0; b < 2; ++b)
; #pragma unroll
;             for (int m = 0; m < 4; ++m)
; #pragma unroll
;                 for (int n = 0; n < 2; ++n) acc[a][b][m][n] = (f32x4){0.f, 0.f, 0.f, 0.f};
;     bf16x8 At[4][2], B0[2][2], B1[2][2];
;     const char* cA = g.a(cur); const char* cB = g.b(cur);
;     S.a_ready(cur);
;     PG8_STAGE(PG8_SB(0, 0), cB, voffB); PG8_STAGE(PG8_SB(0, 1), cB + hstepB, voffB); PG8_STAGE(PG8_SA(0, 0), cA, voffA); PG8_STAGE(PG8_SA(0, 1), cA + hstepA, voffA);
;     if (wr == 1) PG8_BAR;
;     PG8_WAIT_V(2); PG8_BAR;
;     PG8_STAGE(PG8_SB(1, 0), cB + kstep, voffB); PG8_STAGE(PG8_SA(1, 0), cA + kstep, voffA); PG8_STAGE(PG8_SB(1, 1), cB + hstepB + kstep, voffB);
;     PG8_WAIT_V(6); PG8_BAR;
.LBB0_349:
	v_and_b32_e32 v10, 15, v0
	v_or_b32_e32 v11, s48, v10
	v_lshlrev_b32_e32 v12, 6, v11
	v_and_b32_e32 v13, 48, v0
	s_movk_i32 s18, 0x3c0
	v_and_b32_e32 v1, 0xfffffc00, v1
	v_lshlrev_b32_e32 v0, 2, v0
	v_mov_b32_e32 v133, v131
	v_and_or_b32 v12, v12, s18, v13
	v_lshlrev_b32_e32 v11, 2, v11
	v_lshl_or_b32 v10, v10, 6, v13
	v_add_u32_e32 v13, s39, v1
	v_and_b32_e32 v0, 32, v0
	v_readlane_b32 s18, v254, 18
	v_lshl_add_u64 v[2:3], s[12:13], 0, v[130:131]
	v_mov_b32_e32 v137, v131
	v_lshl_add_u64 v[6:7], s[16:17], 0, v[132:133]
	v_and_b32_e32 v11, 32, v11
	v_bitop3_b32 v133, v10, v13, v0 bitop3:0xde
	v_add_u32_e32 v0, s18, v1
	v_lshl_add_u64 v[4:5], s[12:13], 0, v[136:137]
	v_bitop3_b32 v10, v12, v0, v11 bitop3:0xde
	v_lshl_add_u64 v[0:1], v[2:3], 0, s[10:11]
	s_add_i32 m0, s57, 0x18000
	v_mov_b32_e32 v135, v131
	s_waitcnt vmcnt(8)
	s_barrier
	v_lshl_add_u64 v[0:1], v[4:5], 0, s[10:11]
	s_add_i32 m0, s57, 0x1a000
	s_add_i32 s67, s57, 0x8000
	s_add_i32 s70, s57, 0xa000
	v_lshl_add_u64 v[8:9], s[16:17], 0, v[134:135]
	v_lshl_add_u64 v[0:1], v[6:7], 0, s[10:11]
	s_mov_b32 m0, s67
	s_add_u32 s18, s12, 0x4080
	v_lshl_add_u64 v[0:1], v[8:9], 0, s[10:11]
	s_mov_b32 m0, s70
	s_addc_u32 s19, s13, 0
	v_lshl_add_u64 v[0:1], s[18:19], 0, v[130:131]
	s_add_i32 m0, s57, 0x1c000
	s_mov_b64 s[22:23], 0
	v_lshl_add_u64 v[0:1], s[18:19], 0, v[136:137]
	s_add_i32 m0, s57, 0x1e000
	s_mov_b64 s[18:19], -1
	s_waitcnt vmcnt(6)
	v_mov_b32_e32 v0, 0
	s_mov_b64 s[20:21], 0
	v_add_u32_e32 v135, 0, v10
	v_mov_b32_e32 v1, v0
	v_mov_b32_e32 v2, v0
	v_mov_b32_e32 v3, v0
	v_mov_b32_e32 v4, v0
	v_mov_b32_e32 v5, v0
	v_mov_b32_e32 v6, v0
	v_mov_b32_e32 v7, v0
	v_mov_b32_e32 v8, v0
	v_mov_b32_e32 v9, v0
	v_mov_b32_e32 v10, v0
	v_mov_b32_e32 v11, v0
	v_mov_b32_e32 v16, v0
	v_mov_b32_e32 v17, v0
	v_mov_b32_e32 v18, v0
	v_mov_b32_e32 v19, v0
	v_mov_b32_e32 v24, v0
	v_mov_b32_e32 v25, v0
	v_mov_b32_e32 v26, v0
	v_mov_b32_e32 v27, v0
	v_mov_b32_e32 v32, v0
	v_mov_b32_e32 v33, v0
	v_mov_b32_e32 v34, v0
	v_mov_b32_e32 v35, v0
	v_mov_b32_e32 v40, v0
	v_mov_b32_e32 v41, v0
	v_mov_b32_e32 v42, v0
	v_mov_b32_e32 v43, v0
	v_mov_b32_e32 v48, v0
	v_mov_b32_e32 v49, v0
	v_mov_b32_e32 v50, v0
	v_mov_b32_e32 v51, v0
	v_mov_b32_e32 v12, v0
	v_mov_b32_e32 v13, v0
	v_mov_b32_e32 v14, v0
	v_mov_b32_e32 v15, v0
	v_mov_b32_e32 v20, v0
	v_mov_b32_e32 v21, v0
	v_mov_b32_e32 v22, v0
	v_mov_b32_e32 v23, v0
	v_mov_b32_e32 v28, v0
	v_mov_b32_e32 v29, v0
	v_mov_b32_e32 v30, v0
	v_mov_b32_e32 v31, v0
	v_mov_b32_e32 v36, v0
	v_mov_b32_e32 v37, v0
	v_mov_b32_e32 v38, v0
	v_mov_b32_e32 v39, v0
	v_mov_b32_e32 v44, v0
	v_mov_b32_e32 v45, v0
	v_mov_b32_e32 v46, v0
	v_mov_b32_e32 v47, v0
	v_mov_b32_e32 v52, v0
	v_mov_b32_e32 v53, v0
	v_mov_b32_e32 v54, v0
	v_mov_b32_e32 v55, v0
	v_mov_b32_e32 v56, v0
	v_mov_b32_e32 v57, v0
	v_mov_b32_e32 v58, v0
	v_mov_b32_e32 v59, v0
	v_mov_b32_e32 v60, v0
	v_mov_b32_e32 v61, v0
	v_mov_b32_e32 v62, v0
	v_mov_b32_e32 v63, v0
	v_mov_b32_e32 v64, v0
	v_mov_b32_e32 v65, v0
	v_mov_b32_e32 v66, v0
	v_mov_b32_e32 v67, v0
	v_mov_b32_e32 v68, v0
	v_mov_b32_e32 v69, v0
	v_mov_b32_e32 v70, v0
	v_mov_b32_e32 v71, v0
	v_mov_b32_e32 v72, v0
	v_mov_b32_e32 v73, v0
	v_mov_b32_e32 v74, v0
	v_mov_b32_e32 v75, v0
	v_mov_b32_e32 v80, v0
	v_mov_b32_e32 v81, v0
	v_mov_b32_e32 v82, v0
	v_mov_b32_e32 v83, v0
	v_mov_b32_e32 v88, v0
	v_mov_b32_e32 v89, v0
	v_mov_b32_e32 v90, v0
	v_mov_b32_e32 v91, v0
	v_mov_b32_e32 v96, v0
	v_mov_b32_e32 v97, v0
	v_mov_b32_e32 v98, v0
	v_mov_b32_e32 v99, v0
	v_mov_b32_e32 v104, v0
	v_mov_b32_e32 v105, v0
	v_mov_b32_e32 v106, v0
	v_mov_b32_e32 v107, v0
	v_mov_b32_e32 v112, v0
	v_mov_b32_e32 v113, v0
	v_mov_b32_e32 v114, v0
	v_mov_b32_e32 v115, v0
	v_mov_b32_e32 v76, v0
	v_mov_b32_e32 v77, v0
	v_mov_b32_e32 v78, v0
	v_mov_b32_e32 v79, v0
	v_mov_b32_e32 v84, v0
	v_mov_b32_e32 v85, v0
	v_mov_b32_e32 v86, v0
	v_mov_b32_e32 v87, v0
	v_mov_b32_e32 v92, v0
	v_mov_b32_e32 v93, v0
	v_mov_b32_e32 v94, v0
	v_mov_b32_e32 v95, v0
	v_mov_b32_e32 v100, v0
	v_mov_b32_e32 v101, v0
	v_mov_b32_e32 v102, v0
	v_mov_b32_e32 v103, v0
	v_mov_b32_e32 v108, v0
	v_mov_b32_e32 v109, v0
	v_mov_b32_e32 v110, v0
	v_mov_b32_e32 v111, v0
	v_mov_b32_e32 v116, v0
	v_mov_b32_e32 v117, v0
	v_mov_b32_e32 v118, v0
	v_mov_b32_e32 v119, v0
	v_mov_b32_e32 v120, v0
	v_mov_b32_e32 v121, v0
	v_mov_b32_e32 v122, v0
	v_mov_b32_e32 v123, v0
	v_mov_b32_e32 v124, v0
	v_mov_b32_e32 v125, v0
	v_mov_b32_e32 v126, v0
	v_mov_b32_e32 v127, v0
	s_barrier

;     __device__ __forceinline__ unsigned voffA(int R, int C) const { return (unsigned)(R * lda + C) * 2u; }
;     __device__ __forceinline__ unsigned voffB(int R, int C) const { return (unsigned)(R * ldb + C) * 2u; }
;     __device__ __forceinline__ size_t hA() const { return (size_t)HALF * lda * 2; }
;     __device__ __forceinline__ size_t hB() const { return (size_t)HALF * ldb * 2; }
;     __device__ __forceinline__ const char* a(const Unit& u) const { return (const char*)A + (size_t)u.pm * 2 * hA(); }
;     __device__ __forceinline__ const char* b(const Unit& u) const { return (const char*)Bt + (size_t)u.pn * 2 * hB() + (size_t)(u.pm >> gshift) * goff; }
; #define PG8_WAIT_V(n) asm volatile("s_waitcnt vmcnt(" #n ")" ::: "memory")
;     ...
;     for (int i = 0; i < 2; ++i) { int R, C; stage_rc(tid * 16 + i * 8192, R, C); const int Rb = Epi::PERM ? ((R & ~31) + perm32(R & 31)) : R;
;         voffA[i] = g.voffA(R, C); voffB[i] = g.voffB(Rb, C); }
;     const size_t kstep = (size_t)(BK * 2);
;     const size_t hstepA = g.hA(), hstepB = g.hB();
;     const unsigned ldsw = (unsigned)wid * 1024u;
;     const int aoff = lds_byte(wr * 64 + fr, fq * 8), boff = lds_byte(wc * 32 + fr, fq * 8);
;     ...
;     Unit cur, nxt; int ui = 0;
;     if (!S.next(0, cur)) return;
;     f32x4 acc[2][2][4][2];
; #pragma unroll
;     for (int a = 0; a < 2; ++a)
; #pragma unroll
;         for (int b = 0; b < 2; ++b)
; #pragma unroll
;             for (int m = 0; m < 4; ++m)
; #pragma unroll
;                 for (int n = 0; n < 2; ++n) acc[a][b][m][n] = (f32x4){0.f, 0.f, 0.f, 0.f};
;     bf16x8 At[4][2], B0[2][2], B1[2][2];
;     const char* cA = g.a(cur); const char* cB = g.b(cur);
;     S.a_ready(cur);
;     PG8_STAGE(PG8_SB(0, 0), cB, voffB); PG8_STAGE(PG8_SB(0, 1), cB + hstepB, voffB); PG8_STAGE(PG8_SA(0, 0), cA, voffA); PG8_STAGE(PG8_SA(0, 1), cA + hstepA, voffA);
;     if (wr == 1) PG8_BAR;
;     PG8_WAIT_V(2); PG8_BAR;
;     PG8_STAGE(PG8_SB(1, 0), cB + kstep, voffB); PG8_STAGE(PG8_SA(1, 0), cA + kstep, voffA); PG8_STAGE(PG8_SB(1, 1), cB + hstepB + kstep, voffB);
;     PG8_WAIT_V(6); PG8_BAR;
; __global__ void __launch_bounds__(NWAVES * 64, 2) mk_fwd(Args args) {
;     ...
;         pg8::AddrF2 g{trig2, zt}; pg8::StaticOrder S; S.init(64 * 256, 1024, G, (int)blockIdx.x);
;         pg8::EpiY E{y, 1536};
;         pg8::gemm_phase<pg8::EpiY, pg8::StaticOrder, pg8::AddrF2, true>(lds, 512, g, S, E, wave);
.LBB0_523:
	v_lshl_add_u32 v0, v4, 4, s33
	v_ashrrev_i32_e32 v1, 31, v0
	v_lshrrev_b32_e32 v1, 22, v1
	v_add_u32_e32 v1, v0, v1
	v_ashrrev_i32_e32 v1, 10, v1
	v_mul_i32_i24_e32 v2, 0x400, v1
	v_sub_u32_e32 v2, v0, v2
	v_lshrrev_b32_e32 v3, 4, v2
	v_bitop3_b32 v2, v3, v2, 32 bitop3:0x6c
	v_ashrrev_i32_e32 v5, 31, v2
	v_lshrrev_b32_e32 v5, 26, v5
	v_lshlrev_b32_e32 v3, 3, v1
	v_add_u32_e32 v5, v2, v5
	v_and_b32_e32 v3, -16, v3
	v_ashrrev_i32_e32 v6, 6, v5
	v_and_b32_e32 v5, 0xc0, v5
	v_add_u32_e32 v3, v6, v3
	v_sub_u32_e32 v2, v2, v5
	v_mov_b32_e32 v5, 1
	v_lshlrev_b32_e32 v1, 5, v1
	v_ashrrev_i16_sdwa v2, v5, sext(v2) dst_sel:DWORD dst_unused:UNUSED_PAD src0_sel:DWORD src1_sel:BYTE_0
	v_lshlrev_b32_e32 v7, 1, v3
	v_lshrrev_b32_e32 v8, 2, v3
	v_and_b32_e32 v6, 3, v6
	s_mov_b32 s0, 0x3ffe0
	v_and_b32_e32 v1, 32, v1
	v_bfe_i32 v2, v2, 0, 16
	v_and_b32_e32 v7, 24, v7
	v_and_b32_e32 v8, 4, v8
	v_and_or_b32 v6, v3, s0, v6
	v_or3_b32 v6, v6, v8, v7
	v_add_lshl_u32 v1, v1, v2, 1
	v_add_u32_e32 v0, 0x2000, v0
	v_lshl_add_u32 v128, v3, 10, v1
	v_lshl_add_u32 v130, v6, 14, v1
	v_ashrrev_i32_e32 v1, 31, v0
	v_lshrrev_b32_e32 v1, 22, v1
	v_add_u32_e32 v1, v0, v1
	v_ashrrev_i32_e32 v1, 10, v1
	v_mul_i32_i24_e32 v2, 0x400, v1
	v_sub_u32_e32 v0, v0, v2
	v_lshrrev_b32_e32 v2, 4, v0
	v_bitop3_b32 v0, v2, v0, 32 bitop3:0x6c
	v_ashrrev_i32_e32 v3, 31, v0
	v_lshrrev_b32_e32 v3, 26, v3
	v_lshlrev_b32_e32 v2, 3, v1
	v_add_u32_e32 v3, v0, v3
	v_and_b32_e32 v2, -16, v2
	v_ashrrev_i32_e32 v6, 6, v3
	s_ashr_i32 s5, s5, 3
	v_add_u32_e32 v2, v6, v2
	v_and_b32_e32 v6, 3, v6
	v_and_or_b32 v6, v2, s0, v6
	s_add_u32 s0, s94, 0x300000
	s_addc_u32 s1, s95, 0
	s_add_u32 s15, s94, 0x18400000
	s_addc_u32 s30, s95, 0
	s_add_i32 s4, s4, s5
	s_ashr_i32 s5, s4, 31
	s_lshr_b32 s5, s5, 28
	s_add_i32 s5, s4, s5
	s_ashr_i32 s6, s5, 4
	s_and_b32 s5, s5, -16
	s_sub_i32 s4, s4, s5
	s_bfe_i32 s5, s4, 0x80000
	s_bfe_u32 s5, s5, 0x2000d
	s_add_i32 s5, s4, s5
	s_bfe_i32 s7, s5, 0x80000
	s_and_b32 s5, s5, 0xfc
	s_sub_i32 s4, s4, s5
	s_lshl_b32 s6, s6, 2
	s_sext_i32_i8 s4, s4
	s_sext_i32_i16 s7, s7
	s_add_i32 s47, s6, s4
	s_ashr_i32 s49, s7, 2
	s_lshl_b32 s4, s47, 10
	s_and_b32 s4, s4, 0xffffc000
	s_lshl_b32 s5, s49, 12
	v_and_b32_e32 v3, 0xffc0, v3
	s_add_i32 s4, s4, s5
	s_and_b32 s5, s47, 15
	v_sub_u32_e32 v0, v0, v3
	s_or_b32 s4, s4, s5
	v_lshrrev_b16_e32 v3, 7, v0
	s_ashr_i32 s5, s4, 31
	v_and_b32_e32 v3, 1, v3
	s_lshl_b64 s[4:5], s[4:5], 10
	v_add_u16_e32 v0, v0, v3
	s_add_u32 s12, s15, s4
	v_lshlrev_b32_e32 v1, 5, v1
	v_ashrrev_i16_sdwa v0, v5, sext(v0) dst_sel:DWORD dst_unused:UNUSED_PAD src0_sel:DWORD src1_sel:BYTE_0
	v_lshlrev_b32_e32 v3, 1, v2
	v_lshrrev_b32_e32 v5, 2, v2
	s_addc_u32 s13, s30, s5
	s_add_i32 s31, s33, 0
	v_and_b32_e32 v1, 32, v1
	v_bfe_i32 v0, v0, 0, 16
	v_and_b32_e32 v3, 24, v3
	v_and_b32_e32 v5, 4, v5
	s_add_i32 m0, s31, 0x10000
	v_or3_b32 v3, v6, v5, v3
	v_add_lshl_u32 v0, v1, v0, 1
	global_load_lds_dwordx4 v130, s[12:13]
	s_add_i32 m0, s31, 0x12000
	v_lshl_add_u32 v134, v3, 14, v0
	s_add_u32 s4, s12, 0x200000
	global_load_lds_dwordx4 v134, s[12:13]
	s_addc_u32 s5, s13, 0
	s_add_i32 m0, s31, 0x14000
	s_add_i32 s34, s31, 0x2000
	global_load_lds_dwordx4 v130, s[4:5]
	s_add_i32 m0, s31, 0x16000
	v_lshl_add_u32 v132, v2, 10, v0
	global_load_lds_dwordx4 v134, s[4:5]
	s_mov_b32 m0, s31
	s_add_u32 s4, s94, 0x320000
	global_load_lds_dwordx4 v128, s[0:1]
	s_mov_b32 m0, s34
	s_addc_u32 s5, s95, 0
	s_add_i32 s35, s31, 0x4000
	global_load_lds_dwordx4 v132, s[0:1]
	s_mov_b32 m0, s35
	s_add_i32 s36, s31, 0x6000
	global_load_lds_dwordx4 v128, s[4:5]
	s_mov_b32 m0, s36
	v_mov_b32_e32 v131, 0
	global_load_lds_dwordx4 v132, s[4:5]
	s_add_u32 s98, s12, 0x80
	s_addc_u32 s99, s13, 0
	s_add_i32 m0, s31, 0x18000
	s_nop 0
	global_load_lds_dwordx4 v130, s[98:99]
	s_add_i32 m0, s31, 0x1a000
	s_nop 0
	global_load_lds_dwordx4 v134, s[98:99]
	s_add_u32 s98, s94, 0x300080
	s_addc_u32 s99, s95, 0
	s_add_i32 m0, s31, 0x8000
	s_nop 0
	global_load_lds_dwordx4 v128, s[98:99]
	s_add_i32 m0, s31, 0xa000
	s_nop 0
	global_load_lds_dwordx4 v132, s[98:99]
	s_add_u32 s98, s12, 0x200080
	s_addc_u32 s99, s13, 0
	s_add_i32 m0, s31, 0x1c000
	s_nop 0
	global_load_lds_dwordx4 v130, s[98:99]
	s_add_i32 m0, s31, 0x1e000
	s_nop 0
	global_load_lds_dwordx4 v134, s[98:99]
	v_readlane_b32 s4, v254, 16
	v_mov_b32_e32 v135, v131
	s_cmp_eq_u32 s4, 1
	s_mov_b32 s37, 0
	v_lshl_add_u64 v[2:3], s[12:13], 0, v[130:131]
	v_lshl_add_u64 v[0:1], s[12:13], 0, v[134:135]
	v_mov_b32_e32 v129, v131
	s_cselect_b64 s[8:9], -1, 0
	s_cmp_lg_u32 s4, 1
	v_mov_b32_e32 v133, v131
	s_cbranch_scc1 .LBB0_525
	s_barrier
.LBB0_525:
	s_mov_b64 s[4:5], 0x80
	s_add_i32 m0, s31, 0x18000
	v_lshl_add_u64 v[2:3], v[2:3], 0, s[4:5]
	s_waitcnt vmcnt(8)
	s_barrier
	s_add_i32 m0, s31, 0x1a000
	v_lshl_add_u64 v[0:1], v[0:1], 0, s[4:5]
	s_add_u32 s4, s94, 0x300080
	s_addc_u32 s5, s95, 0
	s_add_i32 s38, s31, 0x8000
	v_lshl_add_u64 v[0:1], s[4:5], 0, v[128:129]
	s_mov_b32 m0, s38
	s_add_i32 s39, s31, 0xa000
	v_lshl_add_u64 v[0:1], s[4:5], 0, v[132:133]
	s_add_u32 s4, s12, 0x200080
	s_mov_b32 m0, s39
	s_addc_u32 s5, s13, 0
	s_add_i32 m0, s31, 0x1c000
	v_lshl_add_u64 v[0:1], s[4:5], 0, v[130:131]
	v_lshl_add_u64 v[0:1], s[4:5], 0, v[134:135]
	s_add_i32 m0, s31, 0x1e000
	v_and_b32_e32 v2, 48, v4
	v_and_b32_e32 v0, 15, v4
	v_ashrrev_i32_e32 v1, 6, v4
	v_readlane_b32 s4, v254, 18
	v_lshl_or_b32 v0, v0, 6, v2
	v_lshlrev_b32_e32 v3, 2, v4
	v_lshl_add_u32 v2, v1, 10, s4
	v_readlane_b32 s4, v254, 19
	v_and_b32_e32 v3, 32, v3
	s_waitcnt vmcnt(6)
	v_bitop3_b32 v2, v0, v2, v3 bitop3:0xde
	v_add_lshl_u32 v1, v1, s4, 10
	v_readlane_b32 s4, v254, 14
	s_cmpk_lt_u32 s4, 0x100
	v_bitop3_b32 v129, v0, v1, v3 bitop3:0xde
	s_cselect_b64 s[10:11], -1, 0
	v_readlane_b32 s4, v254, 16
	s_add_i32 s42, 0, 0x10000
	s_add_i32 s43, 0, 0x14000
	s_lshl_b32 s40, s4, 10
	s_ashr_i32 s41, s3, 31
	v_mov_b64_e32 v[136:137], 0x100
	v_mov_b64_e32 v[138:139], 0xff
	v_add_u32_e32 v131, s42, v129
	v_add_u32_e32 v133, s43, v129
	v_add_u32_e32 v135, 0, v2
	s_movk_i32 s44, 0xc00
	s_barrier
	s_branch .LBB0_528

;     __device__ __forceinline__ unsigned voffA(int R, int C) const { return (unsigned)(R * lda + C) * 2u; }
;     __device__ __forceinline__ unsigned voffB(int R, int C) const { return (unsigned)(R * ldb + C) * 2u; }
;     __device__ __forceinline__ size_t hA() const { return (size_t)HALF * lda * 2; }
;     __device__ __forceinline__ size_t hB() const { return (size_t)HALF * ldb * 2; }
;     __device__ __forceinline__ const char* a(const Unit& u) const { return (const char*)A + (size_t)u.pm * 2 * hA(); }
;     __device__ __forceinline__ const char* b(const Unit& u) const { return (const char*)Bt + (size_t)u.pn * 2 * hB() + (size_t)(u.pm >> gshift) * goff; }
;     ...
;     for (int i = 0; i < 2; ++i) { int R, C; stage_rc(tid * 16 + i * 8192, R, C); const int Rb = Epi::PERM ? ((R & ~31) + perm32(R & 31)) : R;
;         voffA[i] = g.voffA(R, C); voffB[i] = g.voffB(Rb, C); }
;     const size_t kstep = (size_t)(BK * 2);
;     const size_t hstepA = g.hA(), hstepB = g.hB();
;     const unsigned ldsw = (unsigned)wid * 1024u;
;     const int aoff = lds_byte(wr * 64 + fr, fq * 8), boff = lds_byte(wc * 32 + fr, fq * 8);
;     ...
;     Unit cur, nxt; int ui = 0;
;     if (!S.next(0, cur)) return;
;     f32x4 acc[2][2][4][2];
; #pragma unroll
;     for (int a = 0; a < 2; ++a)
; #pragma unroll
;         for (int b = 0; b < 2; ++b)
; #pragma unroll
;             for (int m = 0; m < 4; ++m)
; #pragma unroll
;                 for (int n = 0; n < 2; ++n) acc[a][b][m][n] = (f32x4){0.f, 0.f, 0.f, 0.f};
;     bf16x8 At[4][2], B0[2][2], B1[2][2];
;     const char* cA = g.a(cur); const char* cB = g.b(cur);
;     S.a_ready(cur);
;     PG8_STAGE(PG8_SB(0, 0), cB, voffB); PG8_STAGE(PG8_SB(0, 1), cB + hstepB, voffB); PG8_STAGE(PG8_SA(0, 0), cA, voffA); PG8_STAGE(PG8_SA(0, 1), cA + hstepA, voffA);
;     if (wr == 1) PG8_BAR;
;     PG8_WAIT_V(2); PG8_BAR;
;     PG8_STAGE(PG8_SB(1, 0), cB + kstep, voffB); PG8_STAGE(PG8_SA(1, 0), cA + kstep, voffA); PG8_STAGE(PG8_SB(1, 1), cB + hstepB + kstep, voffB);
;     PG8_WAIT_V(6); PG8_BAR;
; __global__ void __launch_bounds__(NWAVES * 64, 2) mk_fwd(Args args) {
;     ...
;         pg8::AddrStd g{y, wo, 1536, 1536, 30, 0u}; pg8::StaticOrder S; S.init(T, 2048, G, (int)blockIdx.x, WGM_O);
;         pg8::EpiResXb E{xb, h1b, ssq1, 2048, 1.0f / 32.0f};
;         pg8::gemm_phase<pg8::EpiResXb, pg8::StaticOrder, pg8::AddrStd, true, 16>(lds, 1536, g, S, E, wave);
.LBB0_604:
	s_add_u32 s66, s94, 0x40000
	s_addc_u32 s67, s95, 0
	s_add_u32 s74, s94, 0x6400000
	s_addc_u32 s75, s95, 0
	s_andn2_b64 vcc, exec, s[0:1]
	s_cbranch_vccnz .LBB0_646
	v_lshl_add_u32 v0, v8, 4, s33
	v_ashrrev_i32_e32 v1, 31, v0
	v_lshrrev_b32_e32 v1, 22, v1
	v_add_u32_e32 v1, v0, v1
	v_ashrrev_i32_e32 v1, 10, v1
	v_mul_i32_i24_e32 v2, 0x400, v1
	v_sub_u32_e32 v2, v0, v2
	v_lshrrev_b32_e32 v3, 4, v2
	v_bitop3_b32 v2, v3, v2, 32 bitop3:0x6c
	v_ashrrev_i32_e32 v4, 31, v2
	v_lshrrev_b32_e32 v4, 26, v4
	v_add_u32_e32 v4, v2, v4
	v_lshlrev_b32_e32 v3, 3, v1
	v_ashrrev_i32_e32 v5, 6, v4
	v_and_b32_e32 v4, 0xc0, v4
	v_and_b32_e32 v3, -16, v3
	v_lshlrev_b32_e32 v1, 5, v1
	v_sub_u32_e32 v2, v2, v4
	v_mov_b32_e32 v4, 1
	v_add_u32_e32 v3, v5, v3
	v_and_b32_e32 v1, 32, v1
	v_ashrrev_i16_sdwa v2, v4, sext(v2) dst_sel:DWORD dst_unused:UNUSED_PAD src0_sel:DWORD src1_sel:BYTE_0
	v_add_u32_sdwa v1, v1, sext(v2) dst_sel:DWORD dst_unused:UNUSED_PAD src0_sel:DWORD src1_sel:WORD_0
	v_lshlrev_b32_e32 v2, 1, v3
	v_lshrrev_b32_e32 v6, 2, v3
	v_and_b32_e32 v5, 3, v5
	s_mov_b32 s0, 0x7fffe0
	v_and_b32_e32 v2, 24, v2
	v_and_b32_e32 v6, 4, v6
	v_and_or_b32 v5, v3, s0, v5
	v_or3_b32 v2, v5, v6, v2
	s_movk_i32 s1, 0x600
	v_mul_lo_u32 v3, v3, s1
	v_mul_u32_u24_e32 v2, 0x600, v2
	v_add_u32_e32 v0, 0x2000, v0
	v_add_lshl_u32 v184, v1, v3, 1
	v_add_lshl_u32 v186, v2, v1, 1
	v_ashrrev_i32_e32 v1, 31, v0
	v_lshrrev_b32_e32 v1, 22, v1
	v_add_u32_e32 v1, v0, v1
	v_ashrrev_i32_e32 v1, 10, v1
	v_mul_i32_i24_e32 v2, 0x400, v1
	v_sub_u32_e32 v0, v0, v2
	v_lshrrev_b32_e32 v2, 4, v0
	v_bitop3_b32 v0, v2, v0, 32 bitop3:0x6c
	v_ashrrev_i32_e32 v3, 31, v0
	v_lshrrev_b32_e32 v3, 26, v3
	v_add_u32_e32 v3, v0, v3
	v_ashrrev_i32_e32 v5, 6, v3
	v_and_b32_e32 v3, 0xffc0, v3
	v_sub_u32_e32 v0, v0, v3
	v_lshrrev_b16_e32 v3, 7, v0
	v_lshlrev_b32_e32 v2, 3, v1
	v_and_b32_e32 v3, 1, v3
	v_and_b32_e32 v2, -16, v2
	v_lshlrev_b32_e32 v1, 5, v1
	v_add_u16_e32 v0, v0, v3
	v_add_u32_e32 v2, v5, v2
	v_and_b32_e32 v1, 32, v1
	v_ashrrev_i16_sdwa v0, v4, sext(v0) dst_sel:DWORD dst_unused:UNUSED_PAD src0_sel:DWORD src1_sel:BYTE_0
	v_and_b32_e32 v4, 3, v5
	v_add_u32_sdwa v0, v1, sext(v0) dst_sel:DWORD dst_unused:UNUSED_PAD src0_sel:DWORD src1_sel:WORD_0
	v_lshlrev_b32_e32 v1, 1, v2
	v_lshrrev_b32_e32 v3, 2, v2
	v_and_or_b32 v4, v2, s0, v4
	v_mul_lo_u32 v2, v2, s1
	s_mul_i32 s1, s14, 0xc0000
	v_readlane_b32 s6, v254, 10
	s_mul_hi_i32 s0, s14, 0xc0000
	v_readlane_b32 s7, v254, 11
	s_add_u32 s16, s6, s1
	v_and_b32_e32 v1, 24, v1
	v_and_b32_e32 v3, 4, v3
	s_addc_u32 s17, s7, s0
	s_add_i32 s34, s33, 0
	v_or3_b32 v1, v4, v3, v1
	s_add_i32 m0, s34, 0x10000
	v_mul_u32_u24_e32 v1, 0x600, v1
	global_load_lds_dwordx4 v186, s[16:17]
	s_add_i32 m0, s34, 0x12000
	v_add_lshl_u32 v190, v1, v0, 1
	s_add_u32 s0, s16, 0x60000
	global_load_lds_dwordx4 v190, s[16:17]
	s_addc_u32 s1, s17, 0
	s_add_i32 m0, s34, 0x14000
	s_mul_i32 s5, s15, 0xc0000
	global_load_lds_dwordx4 v186, s[0:1]
	s_add_i32 m0, s34, 0x16000
	s_mul_hi_i32 s4, s15, 0xc0000
	s_add_u32 s18, s68, s5
	s_addc_u32 s19, s69, s4
	s_add_i32 s35, s34, 0x2000
	global_load_lds_dwordx4 v190, s[0:1]
	s_mov_b32 m0, s34
	s_add_u32 s0, s18, 0x60000
	v_add_lshl_u32 v188, v0, v2, 1
	global_load_lds_dwordx4 v184, s[18:19]
	s_mov_b32 m0, s35
	s_addc_u32 s1, s19, 0
	s_add_i32 s36, s34, 0x4000
	global_load_lds_dwordx4 v188, s[18:19]
	s_mov_b32 m0, s36
	s_add_i32 s37, s34, 0x6000
	global_load_lds_dwordx4 v184, s[0:1]
	s_mov_b32 m0, s37
	v_mov_b32_e32 v187, 0
	global_load_lds_dwordx4 v188, s[0:1]
	s_add_u32 s98, s16, 0x80
	s_addc_u32 s99, s17, 0
	s_add_i32 m0, s34, 0x18000
	s_nop 0
	global_load_lds_dwordx4 v186, s[98:99]
	s_add_i32 m0, s34, 0x1a000
	s_nop 0
	global_load_lds_dwordx4 v190, s[98:99]
	s_add_u32 s98, s18, 0x80
	s_addc_u32 s99, s19, 0
	s_add_i32 m0, s34, 0x8000
	s_nop 0
	global_load_lds_dwordx4 v184, s[98:99]
	s_add_i32 m0, s34, 0xa000
	s_nop 0
	global_load_lds_dwordx4 v188, s[98:99]
	s_add_u32 s98, s16, 0x60080
	s_addc_u32 s99, s17, 0
	s_add_i32 m0, s34, 0x1c000
	s_nop 0
	global_load_lds_dwordx4 v186, s[98:99]
	s_add_i32 m0, s34, 0x1e000
	s_nop 0
	global_load_lds_dwordx4 v190, s[98:99]
	v_readlane_b32 s4, v254, 16
	v_mov_b32_e32 v191, v187
	v_mov_b32_e32 v185, v187
	v_mov_b32_e32 v189, v187
	s_cmp_eq_u32 s4, 1
	s_mov_b32 s38, 0
	v_lshl_add_u64 v[4:5], s[16:17], 0, v[186:187]
	v_lshl_add_u64 v[2:3], s[16:17], 0, v[190:191]
	v_lshl_add_u64 v[0:1], s[18:19], 0, v[184:185]
	s_cselect_b64 s[0:1], -1, 0
	s_cmp_lg_u32 s4, 1
	v_lshl_add_u64 v[6:7], s[18:19], 0, v[188:189]
	s_cbranch_scc1 .LBB0_607
	s_barrier
.LBB0_607:
	s_mov_b64 s[4:5], 0x80
	s_add_i32 m0, s34, 0x18000
	v_lshl_add_u64 v[4:5], v[4:5], 0, s[4:5]
	s_waitcnt vmcnt(8)
	s_barrier
	v_lshl_add_u64 v[2:3], v[2:3], 0, s[4:5]
	s_add_i32 m0, s34, 0x1a000
	s_add_i32 s39, s34, 0x8000
	v_lshl_add_u64 v[0:1], v[0:1], 0, s[4:5]
	s_mov_b32 m0, s39
	s_add_i32 s40, s34, 0xa000
	v_lshl_add_u64 v[0:1], v[6:7], 0, s[4:5]
	s_add_u32 s4, s16, 0x60080
	s_mov_b32 m0, s40
	s_addc_u32 s5, s17, 0
	s_add_i32 m0, s34, 0x1c000
	v_lshl_add_u64 v[0:1], s[4:5], 0, v[186:187]
	v_lshl_add_u64 v[0:1], s[4:5], 0, v[190:191]
	s_add_i32 m0, s34, 0x1e000
	v_and_b32_e32 v4, 48, v8
	v_and_b32_e32 v0, 15, v8
	v_or_b32_e32 v1, s48, v0
	v_lshlrev_b32_e32 v3, 6, v1
	s_movk_i32 s4, 0x3c0
	v_ashrrev_i32_e32 v2, 6, v8
	v_and_or_b32 v3, v3, s4, v4
	v_readlane_b32 s4, v254, 18
	v_lshlrev_b32_e32 v1, 2, v1
	v_and_b32_e32 v1, 32, v1
	v_lshl_add_u32 v5, v2, 10, s4
	v_readlane_b32 s4, v254, 19
	v_bitop3_b32 v1, v3, v5, v1 bitop3:0xde
	v_lshlrev_b32_e32 v3, 2, v8
	v_add_lshl_u32 v2, v2, s4, 10
	v_readlane_b32 s4, v254, 14
	v_lshl_or_b32 v0, v0, 6, v4
	v_and_b32_e32 v3, 32, v3
	s_waitcnt vmcnt(6)
	s_cmpk_lt_u32 s4, 0x100
	v_bitop3_b32 v185, v0, v2, v3 bitop3:0xde
	s_cselect_b64 s[8:9], -1, 0
	s_add_i32 s43, 0, 0x10000
	s_add_i32 s44, 0, 0x14000
	s_ashr_i32 s41, s3, 31
	s_ashr_i32 s42, s2, 31
	v_add_u32_e32 v187, s43, v185
	v_add_u32_e32 v189, s44, v185
	v_add_u32_e32 v191, 0, v1
	v_mbcnt_hi_u32_b32 v252, -1, v253
	s_barrier
	s_branch .LBB0_610
